# EpiS3 row loop x4-unrolled with u-loads re-issued 4 iterations ahead (counted vmcnt)
# speedup vs baseline: 1.0215x; 1.0016x over previous
.LBB0_565:
	v_mov_b32_e32 v130, v191
	s_waitcnt vmcnt(0)
	s_barrier
	s_lshl_b32 s7, s7, 6
	v_and_or_b32 v142, v130, 15, s64
	v_and_b32_e32 v130, 48, v130
	s_add_i32 s7, s7, 0
	v_mul_lo_u32 v142, v142, s56
	v_add3_u32 v130, s7, v130, v142
	v_cvt_pk_bf16_f32 v52, v52, v53
	v_cvt_pk_bf16_f32 v53, v54, v55
	v_cvt_pk_bf16_f32 v54, v48, v49
	v_cvt_pk_bf16_f32 v55, v50, v51
	v_add_u32_e32 v48, 0x10900, v130
	v_cvt_pk_bf16_f32 v36, v36, v37
	v_cvt_pk_bf16_f32 v37, v38, v39
	v_cvt_pk_bf16_f32 v38, v32, v33
	v_cvt_pk_bf16_f32 v39, v34, v35
	v_add_u32_e32 v32, 0x12a00, v130
	v_cvt_pk_bf16_f32 v20, v20, v21
	v_cvt_pk_bf16_f32 v21, v22, v23
	v_cvt_pk_bf16_f32 v22, v16, v17
	v_cvt_pk_bf16_f32 v23, v18, v19
	v_add_u32_e32 v16, 0x14b00, v130
	v_cvt_pk_bf16_f32 v124, v124, v125
	v_cvt_pk_bf16_f32 v125, v126, v127
	v_cvt_pk_bf16_f32 v126, v120, v121
	v_cvt_pk_bf16_f32 v127, v122, v123
	v_cvt_pk_bf16_f32 v116, v116, v117
	v_cvt_pk_bf16_f32 v117, v118, v119
	v_cvt_pk_bf16_f32 v118, v112, v113
	v_cvt_pk_bf16_f32 v119, v114, v115
	v_cvt_pk_bf16_f32 v108, v108, v109
	v_cvt_pk_bf16_f32 v109, v110, v111
	v_cvt_pk_bf16_f32 v110, v104, v105
	v_cvt_pk_bf16_f32 v111, v106, v107
	v_cvt_pk_bf16_f32 v100, v100, v101
	v_cvt_pk_bf16_f32 v101, v102, v103
	v_cvt_pk_bf16_f32 v102, v96, v97
	v_cvt_pk_bf16_f32 v103, v98, v99
	v_cvt_pk_bf16_f32 v92, v92, v93
	v_cvt_pk_bf16_f32 v93, v94, v95
	v_cvt_pk_bf16_f32 v94, v88, v89
	v_cvt_pk_bf16_f32 v95, v90, v91
	v_cvt_pk_bf16_f32 v84, v84, v85
	v_cvt_pk_bf16_f32 v85, v86, v87
	v_cvt_pk_bf16_f32 v86, v80, v81
	v_cvt_pk_bf16_f32 v87, v82, v83
	v_cvt_pk_bf16_f32 v76, v76, v77
	v_cvt_pk_bf16_f32 v77, v78, v79
	v_cvt_pk_bf16_f32 v78, v72, v73
	v_cvt_pk_bf16_f32 v79, v74, v75
	v_cvt_pk_bf16_f32 v68, v68, v69
	v_cvt_pk_bf16_f32 v69, v70, v71
	v_cvt_pk_bf16_f32 v70, v64, v65
	v_cvt_pk_bf16_f32 v71, v66, v67
	v_add_u32_e32 v64, 0x10800, v130
	v_cvt_pk_bf16_f32 v60, v60, v61
	v_cvt_pk_bf16_f32 v61, v62, v63
	v_cvt_pk_bf16_f32 v62, v56, v57
	v_cvt_pk_bf16_f32 v63, v58, v59
	ds_write_b128 v48, v[52:55]
	v_add_u32_e32 v48, 0x12900, v130
	v_cvt_pk_bf16_f32 v44, v44, v45
	v_cvt_pk_bf16_f32 v45, v46, v47
	v_cvt_pk_bf16_f32 v46, v40, v41
	v_cvt_pk_bf16_f32 v47, v42, v43
	ds_write_b128 v32, v[36:39]
	v_add_u32_e32 v32, 0x14a00, v130
	v_cvt_pk_bf16_f32 v28, v28, v29
	v_cvt_pk_bf16_f32 v29, v30, v31
	v_cvt_pk_bf16_f32 v30, v24, v25
	v_cvt_pk_bf16_f32 v31, v26, v27
	ds_write_b128 v16, v[20:23]
	v_add_u32_e32 v16, 0x16b00, v130
	v_cvt_pk_bf16_f32 v12, v12, v13
	v_cvt_pk_bf16_f32 v13, v14, v15
	v_cvt_pk_bf16_f32 v14, v8, v9
	v_cvt_pk_bf16_f32 v15, v10, v11
	v_cvt_pk_bf16_f32 v4, v4, v5
	v_cvt_pk_bf16_f32 v5, v6, v7
	v_cvt_pk_bf16_f32 v6, v0, v1
	v_cvt_pk_bf16_f32 v7, v2, v3
	v_add_u32_e32 v0, 0x16c00, v130
	s_lshl_b32 s10, s44, 4
	ds_write_b128 v130, v[124:127]
	ds_write_b128 v130, v[116:119] offset:256
	ds_write_b128 v130, v[108:111] offset:8448
	ds_write_b128 v130, v[100:103] offset:8704
	ds_write_b128 v130, v[92:95] offset:16896
	ds_write_b128 v130, v[84:87] offset:17152
	ds_write_b128 v130, v[76:79] offset:25344
	ds_write_b128 v130, v[68:71] offset:25600
	ds_write_b128 v64, v[60:63]
	ds_write_b128 v48, v[44:47]
	ds_write_b128 v32, v[28:31]
	ds_write_b128 v16, v[12:15]
	ds_write_b128 v0, v[4:7]
	s_ashr_i32 s11, s10, 31
	s_waitcnt lgkmcnt(0)
	s_barrier
	v_lshl_add_u64 v[4:5], s[10:11], 2, v[132:133]
	global_load_dwordx4 v[0:3], v[4:5], off
	s_nop 0
	global_load_dwordx4 v[4:7], v[4:5], off offset:16
	v_lshl_add_u64 v[10:11], v[128:129], 0, s[46:47]
	v_mad_u64_u32 v[8:9], s[10:11], v10, s59, v[138:139]
	s_and_b32 s7, s54, 0x7000
	s_lshl_b64 s[10:11], s[44:45], 15
	v_or_b32_e32 v130, s7, v137
	v_mad_i32_i24 v9, v11, s59, v9
	v_mov_b32_e32 v11, s11
	v_or_b32_e32 v10, s10, v136
	v_lshl_add_u64 v[10:11], v[10:11], 0, v[130:131]
	v_lshlrev_b64 v[10:11], 5, v[10:11]
	v_lshl_add_u64 v[10:11], v[134:135], 0, v[10:11]
	s_mov_b32 s7, 0
	global_load_dwordx4 v[28:31], v[8:9], off
	v_lshl_add_u64 v[8:9], v[8:9], 0, s[42:43]
	global_load_dwordx4 v[32:35], v[8:9], off
	v_lshl_add_u64 v[8:9], v[8:9], 0, s[42:43]
	global_load_dwordx4 v[36:39], v[8:9], off
	v_lshl_add_u64 v[8:9], v[8:9], 0, s[42:43]
	global_load_dwordx4 v[40:43], v[8:9], off
	v_lshl_add_u64 v[8:9], v[8:9], 0, s[42:43]
.LBB0_566:
	v_add_u32_e32 v16, s7, v152
	ds_read_b128 v[16:19], v16
	s_addk_i32 s7, 0x2100
	s_waitcnt lgkmcnt(0)
	v_lshlrev_b32_e32 v20, 16, v16
	v_and_b32_e32 v21, 0xffff0000, v16
	v_lshlrev_b32_e32 v16, 16, v17
	v_and_b32_e32 v17, 0xffff0000, v17
	v_lshlrev_b32_e32 v22, 16, v18
	v_and_b32_e32 v23, 0xffff0000, v18
	v_lshlrev_b32_e32 v18, 16, v19
	v_and_b32_e32 v19, 0xffff0000, v19
	s_waitcnt vmcnt(3)
	v_lshlrev_b32_e32 v24, 16, v28
	v_and_b32_e32 v25, 0xffff0000, v28
	v_lshlrev_b32_e32 v12, 16, v29
	v_and_b32_e32 v13, 0xffff0000, v29
	v_lshlrev_b32_e32 v26, 16, v30
	v_and_b32_e32 v27, 0xffff0000, v30
	v_lshlrev_b32_e32 v14, 16, v31
	v_and_b32_e32 v15, 0xffff0000, v31
	global_load_dwordx4 v[28:31], v[8:9], off
	v_lshl_add_u64 v[8:9], v[8:9], 0, s[42:43]
	v_pk_fma_f32 v[20:21], v[0:1], v[24:25], v[20:21]
	v_pk_fma_f32 v[12:13], v[2:3], v[12:13], v[16:17]
	v_pk_fma_f32 v[16:17], v[4:5], v[26:27], v[22:23]
	v_pk_fma_f32 v[14:15], v[6:7], v[14:15], v[18:19]
	v_mul_f32_e32 v18, 0x3d372713, v20
	v_mul_f32_e32 v19, 0x3d372713, v21
	v_mul_f32_e32 v22, 0x3d372713, v12
	v_mul_f32_e32 v23, 0x3d372713, v13
	v_mul_f32_e32 v24, 0x3d372713, v16
	v_mul_f32_e32 v25, 0x3d372713, v17
	v_mul_f32_e32 v26, 0x3d372713, v14
	v_mul_f32_e32 v27, 0x3d372713, v15
	v_fma_f32 v18, v20, v18, 1.0
	v_fma_f32 v19, v21, v19, 1.0
	v_fma_f32 v22, v12, v22, 1.0
	v_fma_f32 v23, v13, v23, 1.0
	v_fma_f32 v24, v16, v24, 1.0
	v_fma_f32 v25, v17, v25, 1.0
	v_fma_f32 v26, v14, v26, 1.0
	v_fma_f32 v27, v15, v27, 1.0
	v_mul_f32_e32 v18, v20, v18
	v_mul_f32_e32 v19, v21, v19
	v_mul_f32_e32 v22, v12, v22
	v_mul_f32_e32 v23, v13, v23
	v_mul_f32_e32 v24, v16, v24
	v_mul_f32_e32 v25, v17, v25
	v_mul_f32_e32 v26, v14, v26
	v_mul_f32_e32 v27, v15, v27
	v_mul_f32_e32 v18, 0xc0135761, v18
	v_mul_f32_e32 v19, 0xc0135761, v19
	v_mul_f32_e32 v22, 0xc0135761, v22
	v_mul_f32_e32 v23, 0xc0135761, v23
	v_mul_f32_e32 v24, 0xc0135761, v24
	v_mul_f32_e32 v25, 0xc0135761, v25
	v_mul_f32_e32 v26, 0xc0135761, v26
	v_mul_f32_e32 v27, 0xc0135761, v27
	v_exp_f32_e32 v18, v18
	v_exp_f32_e32 v19, v19
	v_exp_f32_e32 v22, v22
	v_exp_f32_e32 v23, v23
	v_exp_f32_e32 v24, v24
	v_exp_f32_e32 v25, v25
	v_exp_f32_e32 v26, v26
	v_exp_f32_e32 v27, v27
	v_add_f32_e32 v18, 1.0, v18
	v_add_f32_e32 v19, 1.0, v19
	v_add_f32_e32 v22, 1.0, v22
	v_add_f32_e32 v23, 1.0, v23
	v_add_f32_e32 v24, 1.0, v24
	v_add_f32_e32 v25, 1.0, v25
	v_add_f32_e32 v26, 1.0, v26
	v_add_f32_e32 v27, 1.0, v27
	v_rcp_f32_e32 v18, v18
	v_rcp_f32_e32 v19, v19
	v_rcp_f32_e32 v22, v22
	v_rcp_f32_e32 v23, v23
	v_rcp_f32_e32 v24, v24
	v_rcp_f32_e32 v25, v25
	v_rcp_f32_e32 v26, v26
	v_rcp_f32_e32 v27, v27
	v_pk_mul_f32 v[18:19], v[20:21], v[18:19]
	v_pk_mul_f32 v[20:21], v[12:13], v[22:23]
	v_pk_mul_f32 v[16:17], v[16:17], v[24:25]
	v_pk_mul_f32 v[22:23], v[14:15], v[26:27]
	v_cvt_pk_bf16_f32 v12, v18, v19
	v_cvt_pk_bf16_f32 v13, v20, v21
	v_cvt_pk_bf16_f32 v14, v16, v17
	v_cvt_pk_bf16_f32 v15, v22, v23
	global_store_dwordx4 v[10:11], v[12:15], off
	v_lshl_add_u64 v[10:11], v[10:11], 0, s[40:41]
	v_add_u32_e32 v16, s7, v152
	ds_read_b128 v[16:19], v16
	s_addk_i32 s7, 0x2100
	s_waitcnt lgkmcnt(0)
	v_lshlrev_b32_e32 v20, 16, v16
	v_and_b32_e32 v21, 0xffff0000, v16
	v_lshlrev_b32_e32 v16, 16, v17
	v_and_b32_e32 v17, 0xffff0000, v17
	v_lshlrev_b32_e32 v22, 16, v18
	v_and_b32_e32 v23, 0xffff0000, v18
	v_lshlrev_b32_e32 v18, 16, v19
	v_and_b32_e32 v19, 0xffff0000, v19
	s_waitcnt vmcnt(3)
	v_lshlrev_b32_e32 v24, 16, v32
	v_and_b32_e32 v25, 0xffff0000, v32
	v_lshlrev_b32_e32 v12, 16, v33
	v_and_b32_e32 v13, 0xffff0000, v33
	v_lshlrev_b32_e32 v26, 16, v34
	v_and_b32_e32 v27, 0xffff0000, v34
	v_lshlrev_b32_e32 v14, 16, v35
	v_and_b32_e32 v15, 0xffff0000, v35
	global_load_dwordx4 v[32:35], v[8:9], off
	v_lshl_add_u64 v[8:9], v[8:9], 0, s[42:43]
	v_pk_fma_f32 v[20:21], v[0:1], v[24:25], v[20:21]
	v_pk_fma_f32 v[12:13], v[2:3], v[12:13], v[16:17]
	v_pk_fma_f32 v[16:17], v[4:5], v[26:27], v[22:23]
	v_pk_fma_f32 v[14:15], v[6:7], v[14:15], v[18:19]
	v_mul_f32_e32 v18, 0x3d372713, v20
	v_mul_f32_e32 v19, 0x3d372713, v21
	v_mul_f32_e32 v22, 0x3d372713, v12
	v_mul_f32_e32 v23, 0x3d372713, v13
	v_mul_f32_e32 v24, 0x3d372713, v16
	v_mul_f32_e32 v25, 0x3d372713, v17
	v_mul_f32_e32 v26, 0x3d372713, v14
	v_mul_f32_e32 v27, 0x3d372713, v15
	v_fma_f32 v18, v20, v18, 1.0
	v_fma_f32 v19, v21, v19, 1.0
	v_fma_f32 v22, v12, v22, 1.0
	v_fma_f32 v23, v13, v23, 1.0
	v_fma_f32 v24, v16, v24, 1.0
	v_fma_f32 v25, v17, v25, 1.0
	v_fma_f32 v26, v14, v26, 1.0
	v_fma_f32 v27, v15, v27, 1.0
	v_mul_f32_e32 v18, v20, v18
	v_mul_f32_e32 v19, v21, v19
	v_mul_f32_e32 v22, v12, v22
	v_mul_f32_e32 v23, v13, v23
	v_mul_f32_e32 v24, v16, v24
	v_mul_f32_e32 v25, v17, v25
	v_mul_f32_e32 v26, v14, v26
	v_mul_f32_e32 v27, v15, v27
	v_mul_f32_e32 v18, 0xc0135761, v18
	v_mul_f32_e32 v19, 0xc0135761, v19
	v_mul_f32_e32 v22, 0xc0135761, v22
	v_mul_f32_e32 v23, 0xc0135761, v23
	v_mul_f32_e32 v24, 0xc0135761, v24
	v_mul_f32_e32 v25, 0xc0135761, v25
	v_mul_f32_e32 v26, 0xc0135761, v26
	v_mul_f32_e32 v27, 0xc0135761, v27
	v_exp_f32_e32 v18, v18
	v_exp_f32_e32 v19, v19
	v_exp_f32_e32 v22, v22
	v_exp_f32_e32 v23, v23
	v_exp_f32_e32 v24, v24
	v_exp_f32_e32 v25, v25
	v_exp_f32_e32 v26, v26
	v_exp_f32_e32 v27, v27
	v_add_f32_e32 v18, 1.0, v18
	v_add_f32_e32 v19, 1.0, v19
	v_add_f32_e32 v22, 1.0, v22
	v_add_f32_e32 v23, 1.0, v23
	v_add_f32_e32 v24, 1.0, v24
	v_add_f32_e32 v25, 1.0, v25
	v_add_f32_e32 v26, 1.0, v26
	v_add_f32_e32 v27, 1.0, v27
	v_rcp_f32_e32 v18, v18
	v_rcp_f32_e32 v19, v19
	v_rcp_f32_e32 v22, v22
	v_rcp_f32_e32 v23, v23
	v_rcp_f32_e32 v24, v24
	v_rcp_f32_e32 v25, v25
	v_rcp_f32_e32 v26, v26
	v_rcp_f32_e32 v27, v27
	v_pk_mul_f32 v[18:19], v[20:21], v[18:19]
	v_pk_mul_f32 v[20:21], v[12:13], v[22:23]
	v_pk_mul_f32 v[16:17], v[16:17], v[24:25]
	v_pk_mul_f32 v[22:23], v[14:15], v[26:27]
	v_cvt_pk_bf16_f32 v12, v18, v19
	v_cvt_pk_bf16_f32 v13, v20, v21
	v_cvt_pk_bf16_f32 v14, v16, v17
	v_cvt_pk_bf16_f32 v15, v22, v23
	global_store_dwordx4 v[10:11], v[12:15], off
	v_lshl_add_u64 v[10:11], v[10:11], 0, s[40:41]
	v_add_u32_e32 v16, s7, v152
	ds_read_b128 v[16:19], v16
	s_addk_i32 s7, 0x2100
	s_waitcnt lgkmcnt(0)
	v_lshlrev_b32_e32 v20, 16, v16
	v_and_b32_e32 v21, 0xffff0000, v16
	v_lshlrev_b32_e32 v16, 16, v17
	v_and_b32_e32 v17, 0xffff0000, v17
	v_lshlrev_b32_e32 v22, 16, v18
	v_and_b32_e32 v23, 0xffff0000, v18
	v_lshlrev_b32_e32 v18, 16, v19
	v_and_b32_e32 v19, 0xffff0000, v19
	s_waitcnt vmcnt(3)
	v_lshlrev_b32_e32 v24, 16, v36
	v_and_b32_e32 v25, 0xffff0000, v36
	v_lshlrev_b32_e32 v12, 16, v37
	v_and_b32_e32 v13, 0xffff0000, v37
	v_lshlrev_b32_e32 v26, 16, v38
	v_and_b32_e32 v27, 0xffff0000, v38
	v_lshlrev_b32_e32 v14, 16, v39
	v_and_b32_e32 v15, 0xffff0000, v39
	global_load_dwordx4 v[36:39], v[8:9], off
	v_lshl_add_u64 v[8:9], v[8:9], 0, s[42:43]
	v_pk_fma_f32 v[20:21], v[0:1], v[24:25], v[20:21]
	v_pk_fma_f32 v[12:13], v[2:3], v[12:13], v[16:17]
	v_pk_fma_f32 v[16:17], v[4:5], v[26:27], v[22:23]
	v_pk_fma_f32 v[14:15], v[6:7], v[14:15], v[18:19]
	v_mul_f32_e32 v18, 0x3d372713, v20
	v_mul_f32_e32 v19, 0x3d372713, v21
	v_mul_f32_e32 v22, 0x3d372713, v12
	v_mul_f32_e32 v23, 0x3d372713, v13
	v_mul_f32_e32 v24, 0x3d372713, v16
	v_mul_f32_e32 v25, 0x3d372713, v17
	v_mul_f32_e32 v26, 0x3d372713, v14
	v_mul_f32_e32 v27, 0x3d372713, v15
	v_fma_f32 v18, v20, v18, 1.0
	v_fma_f32 v19, v21, v19, 1.0
	v_fma_f32 v22, v12, v22, 1.0
	v_fma_f32 v23, v13, v23, 1.0
	v_fma_f32 v24, v16, v24, 1.0
	v_fma_f32 v25, v17, v25, 1.0
	v_fma_f32 v26, v14, v26, 1.0
	v_fma_f32 v27, v15, v27, 1.0
	v_mul_f32_e32 v18, v20, v18
	v_mul_f32_e32 v19, v21, v19
	v_mul_f32_e32 v22, v12, v22
	v_mul_f32_e32 v23, v13, v23
	v_mul_f32_e32 v24, v16, v24
	v_mul_f32_e32 v25, v17, v25
	v_mul_f32_e32 v26, v14, v26
	v_mul_f32_e32 v27, v15, v27
	v_mul_f32_e32 v18, 0xc0135761, v18
	v_mul_f32_e32 v19, 0xc0135761, v19
	v_mul_f32_e32 v22, 0xc0135761, v22
	v_mul_f32_e32 v23, 0xc0135761, v23
	v_mul_f32_e32 v24, 0xc0135761, v24
	v_mul_f32_e32 v25, 0xc0135761, v25
	v_mul_f32_e32 v26, 0xc0135761, v26
	v_mul_f32_e32 v27, 0xc0135761, v27
	v_exp_f32_e32 v18, v18
	v_exp_f32_e32 v19, v19
	v_exp_f32_e32 v22, v22
	v_exp_f32_e32 v23, v23
	v_exp_f32_e32 v24, v24
	v_exp_f32_e32 v25, v25
	v_exp_f32_e32 v26, v26
	v_exp_f32_e32 v27, v27
	v_add_f32_e32 v18, 1.0, v18
	v_add_f32_e32 v19, 1.0, v19
	v_add_f32_e32 v22, 1.0, v22
	v_add_f32_e32 v23, 1.0, v23
	v_add_f32_e32 v24, 1.0, v24
	v_add_f32_e32 v25, 1.0, v25
	v_add_f32_e32 v26, 1.0, v26
	v_add_f32_e32 v27, 1.0, v27
	v_rcp_f32_e32 v18, v18
	v_rcp_f32_e32 v19, v19
	v_rcp_f32_e32 v22, v22
	v_rcp_f32_e32 v23, v23
	v_rcp_f32_e32 v24, v24
	v_rcp_f32_e32 v25, v25
	v_rcp_f32_e32 v26, v26
	v_rcp_f32_e32 v27, v27
	v_pk_mul_f32 v[18:19], v[20:21], v[18:19]
	v_pk_mul_f32 v[20:21], v[12:13], v[22:23]
	v_pk_mul_f32 v[16:17], v[16:17], v[24:25]
	v_pk_mul_f32 v[22:23], v[14:15], v[26:27]
	v_cvt_pk_bf16_f32 v12, v18, v19
	v_cvt_pk_bf16_f32 v13, v20, v21
	v_cvt_pk_bf16_f32 v14, v16, v17
	v_cvt_pk_bf16_f32 v15, v22, v23
	global_store_dwordx4 v[10:11], v[12:15], off
	v_lshl_add_u64 v[10:11], v[10:11], 0, s[40:41]
	v_add_u32_e32 v16, s7, v152
	ds_read_b128 v[16:19], v16
	s_addk_i32 s7, 0x2100
	s_waitcnt lgkmcnt(0)
	v_lshlrev_b32_e32 v20, 16, v16
	v_and_b32_e32 v21, 0xffff0000, v16
	v_lshlrev_b32_e32 v16, 16, v17
	v_and_b32_e32 v17, 0xffff0000, v17
	v_lshlrev_b32_e32 v22, 16, v18
	v_and_b32_e32 v23, 0xffff0000, v18
	v_lshlrev_b32_e32 v18, 16, v19
	v_and_b32_e32 v19, 0xffff0000, v19
	s_waitcnt vmcnt(3)
	v_lshlrev_b32_e32 v24, 16, v40
	v_and_b32_e32 v25, 0xffff0000, v40
	v_lshlrev_b32_e32 v12, 16, v41
	v_and_b32_e32 v13, 0xffff0000, v41
	v_lshlrev_b32_e32 v26, 16, v42
	v_and_b32_e32 v27, 0xffff0000, v42
	v_lshlrev_b32_e32 v14, 16, v43
	v_and_b32_e32 v15, 0xffff0000, v43
	global_load_dwordx4 v[40:43], v[8:9], off
	v_lshl_add_u64 v[8:9], v[8:9], 0, s[42:43]
	v_pk_fma_f32 v[20:21], v[0:1], v[24:25], v[20:21]
	v_pk_fma_f32 v[12:13], v[2:3], v[12:13], v[16:17]
	v_pk_fma_f32 v[16:17], v[4:5], v[26:27], v[22:23]
	v_pk_fma_f32 v[14:15], v[6:7], v[14:15], v[18:19]
	v_mul_f32_e32 v18, 0x3d372713, v20
	v_mul_f32_e32 v19, 0x3d372713, v21
	v_mul_f32_e32 v22, 0x3d372713, v12
	v_mul_f32_e32 v23, 0x3d372713, v13
	v_mul_f32_e32 v24, 0x3d372713, v16
	v_mul_f32_e32 v25, 0x3d372713, v17
	v_mul_f32_e32 v26, 0x3d372713, v14
	v_mul_f32_e32 v27, 0x3d372713, v15
	v_fma_f32 v18, v20, v18, 1.0
	v_fma_f32 v19, v21, v19, 1.0
	v_fma_f32 v22, v12, v22, 1.0
	v_fma_f32 v23, v13, v23, 1.0
	v_fma_f32 v24, v16, v24, 1.0
	v_fma_f32 v25, v17, v25, 1.0
	v_fma_f32 v26, v14, v26, 1.0
	v_fma_f32 v27, v15, v27, 1.0
	v_mul_f32_e32 v18, v20, v18
	v_mul_f32_e32 v19, v21, v19
	v_mul_f32_e32 v22, v12, v22
	v_mul_f32_e32 v23, v13, v23
	v_mul_f32_e32 v24, v16, v24
	v_mul_f32_e32 v25, v17, v25
	v_mul_f32_e32 v26, v14, v26
	v_mul_f32_e32 v27, v15, v27
	v_mul_f32_e32 v18, 0xc0135761, v18
	v_mul_f32_e32 v19, 0xc0135761, v19
	v_mul_f32_e32 v22, 0xc0135761, v22
	v_mul_f32_e32 v23, 0xc0135761, v23
	v_mul_f32_e32 v24, 0xc0135761, v24
	v_mul_f32_e32 v25, 0xc0135761, v25
	v_mul_f32_e32 v26, 0xc0135761, v26
	v_mul_f32_e32 v27, 0xc0135761, v27
	v_exp_f32_e32 v18, v18
	v_exp_f32_e32 v19, v19
	v_exp_f32_e32 v22, v22
	v_exp_f32_e32 v23, v23
	v_exp_f32_e32 v24, v24
	v_exp_f32_e32 v25, v25
	v_exp_f32_e32 v26, v26
	v_exp_f32_e32 v27, v27
	v_add_f32_e32 v18, 1.0, v18
	v_add_f32_e32 v19, 1.0, v19
	v_add_f32_e32 v22, 1.0, v22
	v_add_f32_e32 v23, 1.0, v23
	v_add_f32_e32 v24, 1.0, v24
	v_add_f32_e32 v25, 1.0, v25
	v_add_f32_e32 v26, 1.0, v26
	v_add_f32_e32 v27, 1.0, v27
	v_rcp_f32_e32 v18, v18
	v_rcp_f32_e32 v19, v19
	v_rcp_f32_e32 v22, v22
	v_rcp_f32_e32 v23, v23
	v_rcp_f32_e32 v24, v24
	v_rcp_f32_e32 v25, v25
	v_rcp_f32_e32 v26, v26
	v_rcp_f32_e32 v27, v27
	v_pk_mul_f32 v[18:19], v[20:21], v[18:19]
	v_pk_mul_f32 v[20:21], v[12:13], v[22:23]
	v_pk_mul_f32 v[16:17], v[16:17], v[24:25]
	v_pk_mul_f32 v[22:23], v[14:15], v[26:27]
	v_cvt_pk_bf16_f32 v12, v18, v19
	v_cvt_pk_bf16_f32 v13, v20, v21
	v_cvt_pk_bf16_f32 v14, v16, v17
	v_cvt_pk_bf16_f32 v15, v22, v23
	global_store_dwordx4 v[10:11], v[12:15], off
	v_lshl_add_u64 v[10:11], v[10:11], 0, s[40:41]
	s_cmp_lg_u32 s7, 0x21000
	s_cbranch_scc1 .LBB0_566
	s_waitcnt vmcnt(0)
	s_waitcnt lgkmcnt(0)
	s_barrier
	s_add_i32 s62, s62, 1
	s_add_u32 s0, s0, s4
	s_addc_u32 s1, s1, s5
	s_add_i32 s54, s54, s55
	s_mov_b64 s[28:29], 0
	s_branch .LBB0_556
